# one static s_setprio 1 for waves 4-7 during the attention phase (reset at its end)
# speedup vs baseline: 1.0102x; 1.0046x over previous
.LBB0_742:
	s_or_b64 exec, exec, s[2:3]
	s_mov_b64 s[0:1], s[66:67]
	s_waitcnt lgkmcnt(0)
	s_barrier
	v_readfirstlane_b32 s100, v180
	s_nop 1
	s_bfe_u32 s100, s100, 0x10008
	s_cmp_eq_u32 s100, 0
	s_cbranch_scc1 .Lattn_noprio
	s_setprio 1
.Lattn_noprio:
	v_mov_b32_e32 v161, v180
	v_writelane_b32 v254, s0, 23
	s_mov_b32 s33, s81
	s_nop 0
	v_writelane_b32 v254, s1, 24
	s_mov_b32 s1, s64
	v_readlane_b32 s0, v254, 0
	s_mov_b32 s3, s0
	s_cmpk_gt_i32 s3, 0xff
	v_writelane_b32 v254, s1, 25
	v_readfirstlane_b32 s0, v161
	s_cbranch_scc1 .LBB0_1018
	s_ashr_i32 s1, s0, 6
	s_lshl_b32 s2, s1, 5
	v_writelane_b32 v254, s2, 26
	s_add_i32 s27, s33, 0x1db00
	s_lshl_b32 s2, s1, 2
	s_add_i32 s28, s33, 0x1db40
	s_add_i32 s2, s27, s2
	s_cmp_lt_u32 s0, 64
	v_writelane_b32 v254, s2, 27
	s_cselect_b64 s[4:5], -1, 0
	v_writelane_b32 v254, s4, 28
	s_add_i32 s0, s33, 0x1db20
	s_add_i32 s2, s33, 0xdb00
	v_writelane_b32 v254, s5, 29
	v_writelane_b32 v254, s0, 30
	s_add_i32 s0, s33, 0x1db08
	v_writelane_b32 v254, s0, 31
	s_add_i32 s0, s33, 0x1db28
	v_writelane_b32 v254, s0, 32
	s_add_i32 s0, s33, 0x1db10
	v_writelane_b32 v254, s0, 33
	s_add_i32 s0, s33, 0x1db30
	v_writelane_b32 v254, s0, 34
	s_add_i32 s0, s33, 0x1db18
	v_writelane_b32 v254, s0, 35
	s_add_i32 s0, s33, 0x1db38
	v_writelane_b32 v254, s0, 36
	s_add_i32 s0, s33, 0x1df08
	v_writelane_b32 v254, s0, 37
	s_add_i32 s0, s33, 0x1df0c
	v_writelane_b32 v254, s0, 38
	s_lshl_b32 s0, s1, 3
	s_mulk_i32 s1, 0x1020
	v_writelane_b32 v254, s2, 39
	s_add_i32 s1, s2, s1
	v_writelane_b32 v254, s1, 40
	v_writelane_b32 v254, s0, 41
	s_addk_i32 s0, 0x185
	v_writelane_b32 v254, s0, 42
	v_writelane_b32 v254, s27, 43
	s_add_i32 s29, s33, 0x1df00
	v_writelane_b32 v254, s28, 44
	s_add_i32 s92, s33, 0x1df04
	v_writelane_b32 v254, s29, 45
	s_branch .LBB0_745

.LBB0_1018:
	s_setprio 0
	s_waitcnt vmcnt(0)
	s_barrier
	s_mov_b64 s[30:31], exec
	v_readlane_b32 s0, v254, 7
	v_readlane_b32 s1, v254, 8
	s_and_b64 s[0:1], s[30:31], s[0:1]
	s_mov_b64 exec, s[0:1]
	s_cbranch_execz .LBB0_1062
	v_readlane_b32 s34, v254, 4
	v_readlane_b32 s0, v254, 3
	v_readlane_b32 s35, v254, 5
	v_readlane_b32 s33, v254, 6
	v_mov_b32_e32 v0, s0
	s_waitcnt vmcnt(0) expcnt(0) lgkmcnt(0)
	ds_read_b32 v2, v0
	v_readlane_b32 s0, v254, 9
	s_waitcnt lgkmcnt(0)
	v_cmp_ne_u32_e32 vcc, 0, v2
	v_mov_b32_e32 v0, s0
	ds_read_b32 v0, v0
	s_cbranch_vccnz .LBB0_1033
	s_add_u32 s0, s34, 0x1000
	s_addc_u32 s1, s35, 0
	s_add_u32 s2, s34, 0x1100
	s_addc_u32 s3, s35, 0
	s_add_u32 s4, s34, 0x1200
	s_addc_u32 s5, s35, 0
	s_add_u32 s6, s34, 0x1300
	s_addc_u32 s7, s35, 0
	s_mov_b32 s26, 1
	s_mov_b64 s[8:9], 0
	s_branch .LBB0_1023
